# P5 residual epilogue: lookahead loads plus write-through (sc1) stores so the output write-back overlaps the epilogue
# baseline (speedup 1.0000x reference)
; __device__ __forceinline__ float bflo(unsigned u) { return __uint_as_float(u << 16); }
; __device__ __forceinline__ float bfhi(unsigned u) { return __uint_as_float(u & 0xffff0000u); }
; __device__ __forceinline__ float dot4(f32x4 v) { return (v[0] * v[0] + v[1] * v[1]) + (v[2] * v[2] + v[3] * v[3]); }
; __device__ __forceinline__ u32x2 pack4(f32x4 v) { u32x2 w; w.x = cvt_pk_bf16(v[0], v[1]); w.y = cvt_pk_bf16(v[2], v[3]); return w; }
; __device__ __forceinline__ float quad_sum(float s) { s += __shfl_xor(s, 16); s += __shfl_xor(s, 32); return s; }
; template <int EK>
; __device__ __forceinline__ void epi_tile(const f32x4 (&acc)[2][2][4][2], const Unit& u, int wr, int wc, int fr, int fq, const EpiArgs& E, const LAS float* rt) {
;     ...
;             } else {
;                 float ss = 0.f;
; #pragma unroll
;                 for (int bj = 0; bj < 2; ++bj) { const int col = u.pn * BM + bj * HALF + wc * 32 + fq * 8;
;                     const u32x4 rb = *(const u32x4*)(E.res + (size_t)row * 1024 + col);
;                     const f32x4 x0 = (f32x4){bflo(rb.x), bfhi(rb.x), bflo(rb.y), bfhi(rb.y)} + acc[ai][bj][m][0];
;                     const f32x4 x1 = (f32x4){bflo(rb.z), bfhi(rb.z), bflo(rb.w), bfhi(rb.w)} + acc[ai][bj][m][1]; ss += dot4(x0) + dot4(x1);
;                     const u32x2 lo = pack4(x0), hi = pack4(x1);
;                     *(u32x4*)(E.ob + (size_t)row * 1024 + col) = (u32x4){lo.x, lo.y, hi.x, hi.y}; }
;                 ss = quad_sum(ss); if (fq == 0) E.stOut[(size_t)row * 16 + u.pn * 4 + wc] = ss;
.LBB0_796:
	v_lshl_add_u32 v148, s3, 8, v1
	v_ashrrev_i32_e32 v149, 31, v148
	v_lshl_or_b32 v146, s45, 8, v153
	v_lshlrev_b64 v[150:151], 11, v[148:149]
	v_lshl_add_u64 v[150:151], s[62:63], 0, v[150:151]
	v_ashrrev_i32_e32 v147, 31, v146
	v_lshl_add_u64 v[166:167], v[146:147], 1, v[150:151]
	global_load_dwordx4 v[158:161], v[166:167], off
	global_load_dwordx4 v[162:165], v[166:167], off offset:256
	v_mov_b64_e32 v[200:201], v[166:167]
	s_mov_b64 s[98:99], 0x8000
	v_lshl_add_u64 v[202:203], v[200:201], 0, s[98:99]
	global_load_dwordx4 v[184:187], v[202:203], off
	global_load_dwordx4 v[188:191], v[202:203], off offset:256
	v_and_b32_e32 v151, 64, v155
	v_xor_b32_e32 v150, 16, v155
	v_add_u32_e32 v151, 64, v151
	v_xor_b32_e32 v156, 32, v155
	v_cmp_lt_i32_e32 vcc, v150, v151
	s_lshl_b32 s38, s45, 2
	s_ashr_i32 s39, s38, 31
	v_cndmask_b32_e32 v150, v155, v150, vcc
	v_cmp_lt_i32_e32 vcc, v156, v151
	s_waitcnt vmcnt(2)
	v_and_b32_e32 v151, 0xffff0000, v158
	v_cndmask_b32_e32 v157, v155, v156, vcc
	v_lshlrev_b32_e32 v156, 2, v150
	v_lshlrev_b32_e32 v150, 16, v158
	v_lshlrev_b32_e32 v158, 16, v159
	v_and_b32_e32 v159, 0xffff0000, v159
	v_lshlrev_b32_e32 v168, 16, v160
	v_and_b32_e32 v169, 0xffff0000, v160
	v_lshlrev_b32_e32 v160, 16, v161
	v_and_b32_e32 v161, 0xffff0000, v161
	v_lshlrev_b32_e32 v170, 16, v162
	v_and_b32_e32 v171, 0xffff0000, v162
	v_lshlrev_b32_e32 v162, 16, v163
	v_and_b32_e32 v163, 0xffff0000, v163
	v_lshlrev_b32_e32 v172, 16, v164
	v_and_b32_e32 v173, 0xffff0000, v164
	v_lshlrev_b32_e32 v164, 16, v165
	v_and_b32_e32 v165, 0xffff0000, v165
	v_pk_add_f32 v[174:175], v[128:129], v[158:159]
	v_pk_add_f32 v[150:151], v[126:127], v[150:151]
	v_pk_add_f32 v[176:177], v[124:125], v[160:161]
	v_pk_add_f32 v[160:161], v[122:123], v[168:169]
	v_pk_add_f32 v[168:169], v[96:97], v[162:163]
	v_pk_add_f32 v[162:163], v[94:95], v[170:171]
	v_pk_add_f32 v[170:171], v[92:93], v[164:165]
	v_pk_add_f32 v[164:165], v[90:91], v[172:173]
	v_mul_f32_e32 v172, v151, v151
	v_mul_f32_e32 v173, v175, v175
	v_mul_f32_e32 v178, v161, v161
	v_mul_f32_e32 v179, v177, v177
	v_cvt_pk_bf16_f32 v158, v150, v151
	v_cvt_pk_bf16_f32 v159, v174, v175
	v_mul_f32_e32 v151, v163, v163
	v_mul_f32_e32 v175, v169, v169
	v_mul_f32_e32 v180, v165, v165
	v_mul_f32_e32 v181, v171, v171
	v_fmac_f32_e32 v172, v150, v150
	v_fmac_f32_e32 v173, v174, v174
	v_fmac_f32_e32 v178, v160, v160
	v_fmac_f32_e32 v179, v176, v176
	v_fmac_f32_e32 v151, v162, v162
	v_fmac_f32_e32 v175, v168, v168
	v_fmac_f32_e32 v180, v164, v164
	v_fmac_f32_e32 v181, v170, v170
	v_add_f32_e32 v150, v172, v173
	v_add_f32_e32 v172, v178, v179
	v_add_f32_e32 v151, v151, v175
	v_add_f32_e32 v173, v180, v181
	v_add_f32_e32 v150, v150, v172
	v_add_f32_e32 v151, v151, v173
	v_add_f32_e32 v150, v150, v151
	ds_bpermute_b32 v151, v156, v150
	v_lshlrev_b32_e32 v157, 2, v157
	v_cvt_pk_bf16_f32 v160, v160, v161
	v_cvt_pk_bf16_f32 v161, v176, v177
	v_cvt_pk_bf16_f32 v162, v162, v163
	s_waitcnt lgkmcnt(0)
	v_add_f32_e32 v150, v150, v151
	ds_bpermute_b32 v151, v157, v150
	global_store_dwordx4 v[166:167], v[158:161], off sc1
	v_cvt_pk_bf16_f32 v163, v168, v169
	v_cvt_pk_bf16_f32 v164, v164, v165
	v_cvt_pk_bf16_f32 v165, v170, v171
	global_store_dwordx4 v[166:167], v[162:165], off offset:256 sc1
	s_and_saveexec_b64 s[40:41], s[4:5]
	s_cbranch_execz .LBB0_798
	v_lshlrev_b64 v[158:159], 6, v[148:149]
	v_lshl_add_u64 v[158:159], s[16:17], 0, v[158:159]
	v_lshl_add_u64 v[158:159], s[38:39], 2, v[158:159]
	s_lshl_b32 s20, s59, 2
	v_lshl_add_u64 v[158:159], v[158:159], 0, s[20:21]
	s_waitcnt lgkmcnt(0)
	v_add_f32_e32 v149, v150, v151
	global_store_dword v[158:159], v149, off sc1
.LBB0_798:
	s_or_b64 exec, exec, s[40:41]
	v_or_b32_e32 v150, 16, v148
	s_waitcnt lgkmcnt(0)
	v_ashrrev_i32_e32 v151, 31, v150
	v_lshlrev_b64 v[158:159], 11, v[150:151]
	v_lshl_add_u64 v[158:159], s[62:63], 0, v[158:159]
	v_lshl_add_u64 v[166:167], v[146:147], 1, v[158:159]
	s_mov_b64 s[98:99], 0x10000
	v_lshl_add_u64 v[202:203], v[200:201], 0, s[98:99]
	global_load_dwordx4 v[192:195], v[202:203], off
	global_load_dwordx4 v[196:199], v[202:203], off offset:256
	s_waitcnt vmcnt(5)
	v_mov_b32_e32 v158, v184
	v_mov_b32_e32 v159, v185
	v_mov_b32_e32 v160, v186
	v_mov_b32_e32 v161, v187
	v_lshlrev_b32_e32 v168, 16, v158
	v_and_b32_e32 v169, 0xffff0000, v158
	v_lshlrev_b32_e32 v158, 16, v159
	v_and_b32_e32 v159, 0xffff0000, v159
	v_lshlrev_b32_e32 v170, 16, v160
	v_and_b32_e32 v171, 0xffff0000, v160
	v_lshlrev_b32_e32 v160, 16, v161
	v_and_b32_e32 v161, 0xffff0000, v161
	v_mov_b32_e32 v162, v188
	v_mov_b32_e32 v163, v189
	v_mov_b32_e32 v164, v190
	v_mov_b32_e32 v165, v191
	v_lshlrev_b32_e32 v172, 16, v162
	v_and_b32_e32 v173, 0xffff0000, v162
	v_lshlrev_b32_e32 v162, 16, v163
	v_and_b32_e32 v163, 0xffff0000, v163
	v_lshlrev_b32_e32 v174, 16, v164
	v_and_b32_e32 v175, 0xffff0000, v164
	v_lshlrev_b32_e32 v164, 16, v165
	v_and_b32_e32 v165, 0xffff0000, v165
	v_pk_add_f32 v[176:177], v[120:121], v[158:159]
	v_pk_add_f32 v[168:169], v[118:119], v[168:169]
	v_pk_add_f32 v[178:179], v[116:117], v[160:161]
	v_pk_add_f32 v[160:161], v[114:115], v[170:171]
	v_pk_add_f32 v[162:163], v[88:89], v[162:163]
	v_pk_add_f32 v[170:171], v[86:87], v[172:173]
	v_pk_add_f32 v[164:165], v[84:85], v[164:165]
	v_pk_add_f32 v[172:173], v[82:83], v[174:175]
	v_mul_f32_e32 v149, v169, v169
	v_mul_f32_e32 v174, v177, v177
	v_mul_f32_e32 v175, v161, v161
	v_mul_f32_e32 v180, v179, v179
	v_cvt_pk_bf16_f32 v158, v168, v169
	v_cvt_pk_bf16_f32 v159, v176, v177
	v_mul_f32_e32 v169, v171, v171
	v_mul_f32_e32 v177, v163, v163
	v_mul_f32_e32 v181, v173, v173
	v_mul_f32_e32 v182, v165, v165
	v_fmac_f32_e32 v149, v168, v168
	v_fmac_f32_e32 v174, v176, v176
	v_fmac_f32_e32 v175, v160, v160
	v_fmac_f32_e32 v180, v178, v178
	v_fmac_f32_e32 v169, v170, v170
	v_fmac_f32_e32 v177, v162, v162
	v_fmac_f32_e32 v181, v172, v172
	v_fmac_f32_e32 v182, v164, v164
	v_add_f32_e32 v149, v149, v174
	v_add_f32_e32 v168, v175, v180
	v_add_f32_e32 v169, v169, v177
	v_add_f32_e32 v174, v181, v182
	v_add_f32_e32 v149, v149, v168
	v_add_f32_e32 v168, v169, v174
	v_add_f32_e32 v149, v149, v168
	ds_bpermute_b32 v168, v156, v149
	v_cvt_pk_bf16_f32 v160, v160, v161
	v_cvt_pk_bf16_f32 v161, v178, v179
	global_store_dwordx4 v[166:167], v[158:161], off sc1
	s_waitcnt lgkmcnt(0)
	v_add_f32_e32 v149, v149, v168
	ds_bpermute_b32 v158, v157, v149
	v_cvt_pk_bf16_f32 v160, v170, v171
	v_cvt_pk_bf16_f32 v161, v162, v163
	v_cvt_pk_bf16_f32 v162, v172, v173
	v_cvt_pk_bf16_f32 v163, v164, v165
	global_store_dwordx4 v[166:167], v[160:163], off offset:256 sc1
	s_and_saveexec_b64 s[40:41], s[4:5]
	s_cbranch_execz .LBB0_800
	v_lshlrev_b64 v[150:151], 6, v[150:151]
	v_lshl_add_u64 v[150:151], s[16:17], 0, v[150:151]
	v_lshl_add_u64 v[150:151], s[38:39], 2, v[150:151]
	s_lshl_b32 s20, s59, 2
	v_lshl_add_u64 v[150:151], v[150:151], 0, s[20:21]
	s_waitcnt lgkmcnt(0)
	v_add_f32_e32 v149, v149, v158
	global_store_dword v[150:151], v149, off sc1
; __device__ __forceinline__ float bflo(unsigned u) { return __uint_as_float(u << 16); }
; __device__ __forceinline__ float bfhi(unsigned u) { return __uint_as_float(u & 0xffff0000u); }
; __device__ __forceinline__ float dot4(f32x4 v) { return (v[0] * v[0] + v[1] * v[1]) + (v[2] * v[2] + v[3] * v[3]); }
; __device__ __forceinline__ u32x2 pack4(f32x4 v) { u32x2 w; w.x = cvt_pk_bf16(v[0], v[1]); w.y = cvt_pk_bf16(v[2], v[3]); return w; }
; __device__ __forceinline__ float quad_sum(float s) { s += __shfl_xor(s, 16); s += __shfl_xor(s, 32); return s; }
; template <int EK>
; __device__ __forceinline__ void epi_tile(const f32x4 (&acc)[2][2][4][2], const Unit& u, int wr, int wc, int fr, int fq, const EpiArgs& E, const LAS float* rt) {
;     ...
;             } else {
;                 float ss = 0.f;
; #pragma unroll
;                 for (int bj = 0; bj < 2; ++bj) { const int col = u.pn * BM + bj * HALF + wc * 32 + fq * 8;
;                     const u32x4 rb = *(const u32x4*)(E.res + (size_t)row * 1024 + col);
;                     const f32x4 x0 = (f32x4){bflo(rb.x), bfhi(rb.x), bflo(rb.y), bfhi(rb.y)} + acc[ai][bj][m][0];
;                     const f32x4 x1 = (f32x4){bflo(rb.z), bfhi(rb.z), bflo(rb.w), bfhi(rb.w)} + acc[ai][bj][m][1]; ss += dot4(x0) + dot4(x1);
;                     const u32x2 lo = pack4(x0), hi = pack4(x1);
;                     *(u32x4*)(E.ob + (size_t)row * 1024 + col) = (u32x4){lo.x, lo.y, hi.x, hi.y}; }
;                 ss = quad_sum(ss); if (fq == 0) E.stOut[(size_t)row * 16 + u.pn * 4 + wc] = ss;
.LBB0_800:
	s_or_b64 exec, exec, s[40:41]
	v_or_b32_e32 v150, 32, v148
	v_ashrrev_i32_e32 v151, 31, v150
	s_waitcnt lgkmcnt(0)
	v_lshlrev_b64 v[158:159], 11, v[150:151]
	v_lshl_add_u64 v[158:159], s[62:63], 0, v[158:159]
	v_lshl_add_u64 v[166:167], v[146:147], 1, v[158:159]
	s_mov_b64 s[98:99], 0x18000
	v_lshl_add_u64 v[202:203], v[200:201], 0, s[98:99]
	global_load_dwordx4 v[184:187], v[202:203], off
	global_load_dwordx4 v[188:191], v[202:203], off offset:256
	s_waitcnt vmcnt(5)
	v_mov_b32_e32 v158, v192
	v_mov_b32_e32 v159, v193
	v_mov_b32_e32 v160, v194
	v_mov_b32_e32 v161, v195
	v_lshlrev_b32_e32 v168, 16, v158
	v_and_b32_e32 v169, 0xffff0000, v158
	v_lshlrev_b32_e32 v158, 16, v159
	v_and_b32_e32 v159, 0xffff0000, v159
	v_lshlrev_b32_e32 v170, 16, v160
	v_and_b32_e32 v171, 0xffff0000, v160
	v_lshlrev_b32_e32 v160, 16, v161
	v_and_b32_e32 v161, 0xffff0000, v161
	v_mov_b32_e32 v162, v196
	v_mov_b32_e32 v163, v197
	v_mov_b32_e32 v164, v198
	v_mov_b32_e32 v165, v199
	v_lshlrev_b32_e32 v172, 16, v162
	v_and_b32_e32 v173, 0xffff0000, v162
	v_lshlrev_b32_e32 v162, 16, v163
	v_and_b32_e32 v163, 0xffff0000, v163
	v_lshlrev_b32_e32 v174, 16, v164
	v_and_b32_e32 v175, 0xffff0000, v164
	v_lshlrev_b32_e32 v164, 16, v165
	v_and_b32_e32 v165, 0xffff0000, v165
	v_pk_add_f32 v[176:177], v[112:113], v[158:159]
	v_pk_add_f32 v[168:169], v[110:111], v[168:169]
	v_pk_add_f32 v[178:179], v[108:109], v[160:161]
	v_pk_add_f32 v[160:161], v[106:107], v[170:171]
	v_pk_add_f32 v[162:163], v[80:81], v[162:163]
	v_pk_add_f32 v[170:171], v[78:79], v[172:173]
	v_pk_add_f32 v[164:165], v[76:77], v[164:165]
	v_pk_add_f32 v[172:173], v[74:75], v[174:175]
	v_mul_f32_e32 v149, v169, v169
	v_mul_f32_e32 v174, v177, v177
	v_mul_f32_e32 v175, v161, v161
	v_mul_f32_e32 v180, v179, v179
	v_cvt_pk_bf16_f32 v158, v168, v169
	v_cvt_pk_bf16_f32 v159, v176, v177
	v_mul_f32_e32 v169, v171, v171
	v_mul_f32_e32 v177, v163, v163
	v_mul_f32_e32 v181, v173, v173
	v_mul_f32_e32 v182, v165, v165
	v_fmac_f32_e32 v149, v168, v168
	v_fmac_f32_e32 v174, v176, v176
	v_fmac_f32_e32 v175, v160, v160
	v_fmac_f32_e32 v180, v178, v178
	v_fmac_f32_e32 v169, v170, v170
	v_fmac_f32_e32 v177, v162, v162
	v_fmac_f32_e32 v181, v172, v172
	v_fmac_f32_e32 v182, v164, v164
	v_add_f32_e32 v149, v149, v174
	v_add_f32_e32 v168, v175, v180
	v_add_f32_e32 v169, v169, v177
	v_add_f32_e32 v174, v181, v182
	v_add_f32_e32 v149, v149, v168
	v_add_f32_e32 v168, v169, v174
	v_add_f32_e32 v149, v149, v168
	ds_bpermute_b32 v168, v156, v149
	v_cvt_pk_bf16_f32 v160, v160, v161
	v_cvt_pk_bf16_f32 v161, v178, v179
	global_store_dwordx4 v[166:167], v[158:161], off sc1
	s_waitcnt lgkmcnt(0)
	v_add_f32_e32 v149, v149, v168
	ds_bpermute_b32 v158, v157, v149
	v_cvt_pk_bf16_f32 v160, v170, v171
	v_cvt_pk_bf16_f32 v161, v162, v163
	v_cvt_pk_bf16_f32 v162, v172, v173
	v_cvt_pk_bf16_f32 v163, v164, v165
	global_store_dwordx4 v[166:167], v[160:163], off offset:256 sc1
	s_and_saveexec_b64 s[40:41], s[4:5]
	s_load_dwordx16 s[80:95], s[0:1], 0x40
	s_waitcnt lgkmcnt(0)
	s_mov_b64 s[48:49], s[92:93]
	s_mov_b64 s[50:51], s[94:95]
	s_mov_b64 s[46:47], s[90:91]
	s_cbranch_execz .LBB0_802
	v_lshlrev_b64 v[150:151], 6, v[150:151]
	v_lshl_add_u64 v[150:151], s[16:17], 0, v[150:151]
	v_lshl_add_u64 v[150:151], s[38:39], 2, v[150:151]
	s_lshl_b32 s20, s59, 2
	v_lshl_add_u64 v[150:151], v[150:151], 0, s[20:21]
	v_add_f32_e32 v149, v149, v158
	global_store_dword v[150:151], v149, off sc1
.LBB0_802:
	s_or_b64 exec, exec, s[40:41]
	v_or_b32_e32 v150, 48, v148
	v_ashrrev_i32_e32 v151, 31, v150
	v_lshlrev_b64 v[158:159], 11, v[150:151]
	v_lshl_add_u64 v[158:159], s[62:63], 0, v[158:159]
	v_lshl_add_u64 v[166:167], v[146:147], 1, v[158:159]
	s_mov_b64 s[98:99], 0x40000
	v_lshl_add_u64 v[202:203], v[200:201], 0, s[98:99]
	global_load_dwordx4 v[192:195], v[202:203], off
	global_load_dwordx4 v[196:199], v[202:203], off offset:256
	s_waitcnt vmcnt(5)
	v_mov_b32_e32 v158, v184
	v_mov_b32_e32 v159, v185
	v_mov_b32_e32 v160, v186
	v_mov_b32_e32 v161, v187
	v_lshlrev_b32_e32 v168, 16, v158
	v_and_b32_e32 v169, 0xffff0000, v158
	v_lshlrev_b32_e32 v158, 16, v159
	v_and_b32_e32 v159, 0xffff0000, v159
	v_lshlrev_b32_e32 v170, 16, v160
	v_and_b32_e32 v171, 0xffff0000, v160
	v_lshlrev_b32_e32 v160, 16, v161
	v_and_b32_e32 v161, 0xffff0000, v161
	v_mov_b32_e32 v162, v188
	v_mov_b32_e32 v163, v189
	v_mov_b32_e32 v164, v190
	v_mov_b32_e32 v165, v191
	v_lshlrev_b32_e32 v172, 16, v162
	v_and_b32_e32 v173, 0xffff0000, v162
	v_lshlrev_b32_e32 v162, 16, v163
	v_and_b32_e32 v163, 0xffff0000, v163
	v_lshlrev_b32_e32 v174, 16, v164
	v_and_b32_e32 v175, 0xffff0000, v164
	v_lshlrev_b32_e32 v164, 16, v165
	v_and_b32_e32 v165, 0xffff0000, v165
	v_pk_add_f32 v[176:177], v[104:105], v[158:159]
	v_pk_add_f32 v[168:169], v[102:103], v[168:169]
	v_pk_add_f32 v[178:179], v[100:101], v[160:161]
	v_pk_add_f32 v[160:161], v[98:99], v[170:171]
	v_pk_add_f32 v[162:163], v[72:73], v[162:163]
	v_pk_add_f32 v[170:171], v[70:71], v[172:173]
	v_pk_add_f32 v[164:165], v[68:69], v[164:165]
	v_pk_add_f32 v[172:173], v[66:67], v[174:175]
	v_mul_f32_e32 v149, v169, v169
	v_mul_f32_e32 v174, v177, v177
	v_mul_f32_e32 v175, v161, v161
	v_mul_f32_e32 v180, v179, v179
	v_cvt_pk_bf16_f32 v158, v168, v169
	v_cvt_pk_bf16_f32 v159, v176, v177
	v_mul_f32_e32 v169, v171, v171
	v_mul_f32_e32 v177, v163, v163
	v_mul_f32_e32 v181, v173, v173
	v_mul_f32_e32 v182, v165, v165
	v_fmac_f32_e32 v149, v168, v168
	v_fmac_f32_e32 v174, v176, v176
	v_fmac_f32_e32 v175, v160, v160
	v_fmac_f32_e32 v180, v178, v178
	v_fmac_f32_e32 v169, v170, v170
	v_fmac_f32_e32 v177, v162, v162
	v_fmac_f32_e32 v181, v172, v172
	v_fmac_f32_e32 v182, v164, v164
	v_add_f32_e32 v149, v149, v174
	v_add_f32_e32 v168, v175, v180
	v_add_f32_e32 v169, v169, v177
	v_add_f32_e32 v174, v181, v182
	v_add_f32_e32 v149, v149, v168
	v_add_f32_e32 v168, v169, v174
	v_add_f32_e32 v149, v149, v168
	ds_bpermute_b32 v168, v156, v149
	v_cvt_pk_bf16_f32 v160, v160, v161
	v_cvt_pk_bf16_f32 v161, v178, v179
	global_store_dwordx4 v[166:167], v[158:161], off sc1
	s_waitcnt lgkmcnt(0)
	v_add_f32_e32 v149, v149, v168
	ds_bpermute_b32 v158, v157, v149
	v_cvt_pk_bf16_f32 v160, v170, v171
	v_cvt_pk_bf16_f32 v161, v162, v163
	v_cvt_pk_bf16_f32 v162, v172, v173
	v_cvt_pk_bf16_f32 v163, v164, v165
	global_store_dwordx4 v[166:167], v[160:163], off offset:256 sc1
	s_and_saveexec_b64 s[40:41], s[4:5]
	s_cbranch_execz .LBB0_804
	v_lshlrev_b64 v[150:151], 6, v[150:151]
	v_lshl_add_u64 v[150:151], s[16:17], 0, v[150:151]
	v_lshl_add_u64 v[150:151], s[38:39], 2, v[150:151]
	s_lshl_b32 s20, s59, 2
	v_lshl_add_u64 v[150:151], v[150:151], 0, s[20:21]
	s_waitcnt lgkmcnt(0)
	v_add_f32_e32 v149, v149, v158
	global_store_dword v[150:151], v149, off sc1
; __device__ __forceinline__ float bflo(unsigned u) { return __uint_as_float(u << 16); }
; __device__ __forceinline__ float bfhi(unsigned u) { return __uint_as_float(u & 0xffff0000u); }
; __device__ __forceinline__ float dot4(f32x4 v) { return (v[0] * v[0] + v[1] * v[1]) + (v[2] * v[2] + v[3] * v[3]); }
; __device__ __forceinline__ u32x2 pack4(f32x4 v) { u32x2 w; w.x = cvt_pk_bf16(v[0], v[1]); w.y = cvt_pk_bf16(v[2], v[3]); return w; }
; __device__ __forceinline__ float quad_sum(float s) { s += __shfl_xor(s, 16); s += __shfl_xor(s, 32); return s; }
; template <int EK>
; __device__ __forceinline__ void epi_tile(const f32x4 (&acc)[2][2][4][2], const Unit& u, int wr, int wc, int fr, int fq, const EpiArgs& E, const LAS float* rt) {
;     ...
;             } else {
;                 float ss = 0.f;
; #pragma unroll
;                 for (int bj = 0; bj < 2; ++bj) { const int col = u.pn * BM + bj * HALF + wc * 32 + fq * 8;
;                     const u32x4 rb = *(const u32x4*)(E.res + (size_t)row * 1024 + col);
;                     const f32x4 x0 = (f32x4){bflo(rb.x), bfhi(rb.x), bflo(rb.y), bfhi(rb.y)} + acc[ai][bj][m][0];
;                     const f32x4 x1 = (f32x4){bflo(rb.z), bfhi(rb.z), bflo(rb.w), bfhi(rb.w)} + acc[ai][bj][m][1]; ss += dot4(x0) + dot4(x1);
;                     const u32x2 lo = pack4(x0), hi = pack4(x1);
;                     *(u32x4*)(E.ob + (size_t)row * 1024 + col) = (u32x4){lo.x, lo.y, hi.x, hi.y}; }
;                 ss = quad_sum(ss); if (fq == 0) E.stOut[(size_t)row * 16 + u.pn * 4 + wc] = ss;
.LBB0_804:
	s_or_b64 exec, exec, s[40:41]
	v_add_u32_e32 v150, 0x80, v148
	v_ashrrev_i32_e32 v151, 31, v150
	s_waitcnt lgkmcnt(0)
	v_lshlrev_b64 v[158:159], 11, v[150:151]
	v_lshl_add_u64 v[158:159], s[62:63], 0, v[158:159]
	v_lshl_add_u64 v[166:167], v[146:147], 1, v[158:159]
	s_mov_b64 s[98:99], 0x48000
	v_lshl_add_u64 v[202:203], v[200:201], 0, s[98:99]
	global_load_dwordx4 v[184:187], v[202:203], off
	global_load_dwordx4 v[188:191], v[202:203], off offset:256
	s_waitcnt vmcnt(5)
	v_mov_b32_e32 v158, v192
	v_mov_b32_e32 v159, v193
	v_mov_b32_e32 v160, v194
	v_mov_b32_e32 v161, v195
	v_lshlrev_b32_e32 v168, 16, v158
	v_and_b32_e32 v169, 0xffff0000, v158
	v_lshlrev_b32_e32 v158, 16, v159
	v_and_b32_e32 v159, 0xffff0000, v159
	v_lshlrev_b32_e32 v170, 16, v160
	v_and_b32_e32 v171, 0xffff0000, v160
	v_lshlrev_b32_e32 v160, 16, v161
	v_and_b32_e32 v161, 0xffff0000, v161
	v_mov_b32_e32 v162, v196
	v_mov_b32_e32 v163, v197
	v_mov_b32_e32 v164, v198
	v_mov_b32_e32 v165, v199
	v_lshlrev_b32_e32 v172, 16, v162
	v_and_b32_e32 v173, 0xffff0000, v162
	v_lshlrev_b32_e32 v162, 16, v163
	v_and_b32_e32 v163, 0xffff0000, v163
	v_lshlrev_b32_e32 v174, 16, v164
	v_and_b32_e32 v175, 0xffff0000, v164
	v_lshlrev_b32_e32 v164, 16, v165
	v_and_b32_e32 v165, 0xffff0000, v165
	v_pk_add_f32 v[176:177], v[64:65], v[158:159]
	v_pk_add_f32 v[168:169], v[62:63], v[168:169]
	v_pk_add_f32 v[178:179], v[60:61], v[160:161]
	v_pk_add_f32 v[160:161], v[58:59], v[170:171]
	v_pk_add_f32 v[162:163], v[32:33], v[162:163]
	v_pk_add_f32 v[170:171], v[30:31], v[172:173]
	v_pk_add_f32 v[164:165], v[28:29], v[164:165]
	v_pk_add_f32 v[172:173], v[26:27], v[174:175]
	v_mul_f32_e32 v149, v169, v169
	v_mul_f32_e32 v174, v177, v177
	v_mul_f32_e32 v175, v161, v161
	v_mul_f32_e32 v180, v179, v179
	v_cvt_pk_bf16_f32 v158, v168, v169
	v_cvt_pk_bf16_f32 v159, v176, v177
	v_mul_f32_e32 v169, v171, v171
	v_mul_f32_e32 v177, v163, v163
	v_mul_f32_e32 v181, v173, v173
	v_mul_f32_e32 v182, v165, v165
	v_fmac_f32_e32 v149, v168, v168
	v_fmac_f32_e32 v174, v176, v176
	v_fmac_f32_e32 v175, v160, v160
	v_fmac_f32_e32 v180, v178, v178
	v_fmac_f32_e32 v169, v170, v170
	v_fmac_f32_e32 v177, v162, v162
	v_fmac_f32_e32 v181, v172, v172
	v_fmac_f32_e32 v182, v164, v164
	v_add_f32_e32 v149, v149, v174
	v_add_f32_e32 v168, v175, v180
	v_add_f32_e32 v169, v169, v177
	v_add_f32_e32 v174, v181, v182
	v_add_f32_e32 v149, v149, v168
	v_add_f32_e32 v168, v169, v174
	v_add_f32_e32 v149, v149, v168
	ds_bpermute_b32 v168, v156, v149
	v_cvt_pk_bf16_f32 v160, v160, v161
	v_cvt_pk_bf16_f32 v161, v178, v179
	global_store_dwordx4 v[166:167], v[158:161], off sc1
	s_waitcnt lgkmcnt(0)
	v_add_f32_e32 v149, v149, v168
	ds_bpermute_b32 v158, v157, v149
	v_cvt_pk_bf16_f32 v160, v170, v171
	v_cvt_pk_bf16_f32 v161, v162, v163
	v_cvt_pk_bf16_f32 v162, v172, v173
	v_cvt_pk_bf16_f32 v163, v164, v165
	global_store_dwordx4 v[166:167], v[160:163], off offset:256 sc1
	s_and_saveexec_b64 s[40:41], s[4:5]
	s_cbranch_execz .LBB0_806
	v_lshlrev_b64 v[150:151], 6, v[150:151]
	v_lshl_add_u64 v[150:151], s[16:17], 0, v[150:151]
	v_lshl_add_u64 v[150:151], s[38:39], 2, v[150:151]
	s_lshl_b32 s20, s59, 2
	v_lshl_add_u64 v[150:151], v[150:151], 0, s[20:21]
	s_waitcnt lgkmcnt(0)
	v_add_f32_e32 v149, v149, v158
	global_store_dword v[150:151], v149, off sc1
.LBB0_806:
	s_or_b64 exec, exec, s[40:41]
	v_add_u32_e32 v150, 0x90, v148
	v_ashrrev_i32_e32 v151, 31, v150
	s_waitcnt lgkmcnt(0)
	v_lshlrev_b64 v[158:159], 11, v[150:151]
	v_lshl_add_u64 v[158:159], s[62:63], 0, v[158:159]
	v_lshl_add_u64 v[166:167], v[146:147], 1, v[158:159]
	s_mov_b64 s[98:99], 0x50000
	v_lshl_add_u64 v[202:203], v[200:201], 0, s[98:99]
	global_load_dwordx4 v[192:195], v[202:203], off
	global_load_dwordx4 v[196:199], v[202:203], off offset:256
	s_waitcnt vmcnt(5)
	v_mov_b32_e32 v158, v184
	v_mov_b32_e32 v159, v185
	v_mov_b32_e32 v160, v186
	v_mov_b32_e32 v161, v187
	v_lshlrev_b32_e32 v168, 16, v158
	v_and_b32_e32 v169, 0xffff0000, v158
	v_lshlrev_b32_e32 v158, 16, v159
	v_and_b32_e32 v159, 0xffff0000, v159
	v_lshlrev_b32_e32 v170, 16, v160
	v_and_b32_e32 v171, 0xffff0000, v160
	v_lshlrev_b32_e32 v160, 16, v161
	v_and_b32_e32 v161, 0xffff0000, v161
	v_mov_b32_e32 v162, v188
	v_mov_b32_e32 v163, v189
	v_mov_b32_e32 v164, v190
	v_mov_b32_e32 v165, v191
	v_lshlrev_b32_e32 v172, 16, v162
	v_and_b32_e32 v173, 0xffff0000, v162
	v_lshlrev_b32_e32 v162, 16, v163
	v_and_b32_e32 v163, 0xffff0000, v163
	v_lshlrev_b32_e32 v174, 16, v164
	v_and_b32_e32 v175, 0xffff0000, v164
	v_lshlrev_b32_e32 v164, 16, v165
	v_and_b32_e32 v165, 0xffff0000, v165
	v_pk_add_f32 v[176:177], v[56:57], v[158:159]
	v_pk_add_f32 v[168:169], v[54:55], v[168:169]
	v_pk_add_f32 v[178:179], v[52:53], v[160:161]
	v_pk_add_f32 v[160:161], v[50:51], v[170:171]
	v_pk_add_f32 v[162:163], v[24:25], v[162:163]
	v_pk_add_f32 v[170:171], v[22:23], v[172:173]
	v_pk_add_f32 v[164:165], v[20:21], v[164:165]
	v_pk_add_f32 v[172:173], v[18:19], v[174:175]
	v_mul_f32_e32 v149, v169, v169
	v_mul_f32_e32 v174, v177, v177
	v_mul_f32_e32 v175, v161, v161
	v_mul_f32_e32 v180, v179, v179
	v_cvt_pk_bf16_f32 v158, v168, v169
	v_cvt_pk_bf16_f32 v159, v176, v177
	v_mul_f32_e32 v169, v171, v171
	v_mul_f32_e32 v177, v163, v163
	v_mul_f32_e32 v181, v173, v173
	v_mul_f32_e32 v182, v165, v165
	v_fmac_f32_e32 v149, v168, v168
	v_fmac_f32_e32 v174, v176, v176
	v_fmac_f32_e32 v175, v160, v160
	v_fmac_f32_e32 v180, v178, v178
	v_fmac_f32_e32 v169, v170, v170
	v_fmac_f32_e32 v177, v162, v162
	v_fmac_f32_e32 v181, v172, v172
	v_fmac_f32_e32 v182, v164, v164
	v_add_f32_e32 v149, v149, v174
	v_add_f32_e32 v168, v175, v180
	v_add_f32_e32 v169, v169, v177
	v_add_f32_e32 v174, v181, v182
	v_add_f32_e32 v149, v149, v168
	v_add_f32_e32 v168, v169, v174
	v_add_f32_e32 v149, v149, v168
	ds_bpermute_b32 v168, v156, v149
	v_cvt_pk_bf16_f32 v160, v160, v161
	v_cvt_pk_bf16_f32 v161, v178, v179
	global_store_dwordx4 v[166:167], v[158:161], off sc1
	s_waitcnt lgkmcnt(0)
	v_add_f32_e32 v149, v149, v168
	ds_bpermute_b32 v158, v157, v149
	v_cvt_pk_bf16_f32 v160, v170, v171
	v_cvt_pk_bf16_f32 v161, v162, v163
	v_cvt_pk_bf16_f32 v162, v172, v173
	v_cvt_pk_bf16_f32 v163, v164, v165
	global_store_dwordx4 v[166:167], v[160:163], off offset:256 sc1
	s_and_saveexec_b64 s[40:41], s[4:5]
	s_cbranch_execz .LBB0_808
	v_lshlrev_b64 v[150:151], 6, v[150:151]
	v_lshl_add_u64 v[150:151], s[16:17], 0, v[150:151]
	v_lshl_add_u64 v[150:151], s[38:39], 2, v[150:151]
	s_lshl_b32 s20, s59, 2
	v_lshl_add_u64 v[150:151], v[150:151], 0, s[20:21]
	s_waitcnt lgkmcnt(0)
	v_add_f32_e32 v149, v149, v158
	global_store_dword v[150:151], v149, off sc1
; __device__ __forceinline__ float bflo(unsigned u) { return __uint_as_float(u << 16); }
; __device__ __forceinline__ float bfhi(unsigned u) { return __uint_as_float(u & 0xffff0000u); }
; __device__ __forceinline__ float dot4(f32x4 v) { return (v[0] * v[0] + v[1] * v[1]) + (v[2] * v[2] + v[3] * v[3]); }
; __device__ __forceinline__ u32x2 pack4(f32x4 v) { u32x2 w; w.x = cvt_pk_bf16(v[0], v[1]); w.y = cvt_pk_bf16(v[2], v[3]); return w; }
; __device__ __forceinline__ float quad_sum(float s) { s += __shfl_xor(s, 16); s += __shfl_xor(s, 32); return s; }
; template <int EK>
; __device__ __forceinline__ void epi_tile(const f32x4 (&acc)[2][2][4][2], const Unit& u, int wr, int wc, int fr, int fq, const EpiArgs& E, const LAS float* rt) {
;     ...
;             } else {
;                 float ss = 0.f;
; #pragma unroll
;                 for (int bj = 0; bj < 2; ++bj) { const int col = u.pn * BM + bj * HALF + wc * 32 + fq * 8;
;                     const u32x4 rb = *(const u32x4*)(E.res + (size_t)row * 1024 + col);
;                     const f32x4 x0 = (f32x4){bflo(rb.x), bfhi(rb.x), bflo(rb.y), bfhi(rb.y)} + acc[ai][bj][m][0];
;                     const f32x4 x1 = (f32x4){bflo(rb.z), bfhi(rb.z), bflo(rb.w), bfhi(rb.w)} + acc[ai][bj][m][1]; ss += dot4(x0) + dot4(x1);
;                     const u32x2 lo = pack4(x0), hi = pack4(x1);
;                     *(u32x4*)(E.ob + (size_t)row * 1024 + col) = (u32x4){lo.x, lo.y, hi.x, hi.y}; }
;                 ss = quad_sum(ss); if (fq == 0) E.stOut[(size_t)row * 16 + u.pn * 4 + wc] = ss;
.LBB0_808:
	s_or_b64 exec, exec, s[40:41]
	v_add_u32_e32 v150, 0xa0, v148
	v_ashrrev_i32_e32 v151, 31, v150
	s_waitcnt lgkmcnt(0)
	v_lshlrev_b64 v[158:159], 11, v[150:151]
	v_lshl_add_u64 v[158:159], s[62:63], 0, v[158:159]
	v_lshl_add_u64 v[166:167], v[146:147], 1, v[158:159]
	s_mov_b64 s[98:99], 0x58000
	v_lshl_add_u64 v[202:203], v[200:201], 0, s[98:99]
	global_load_dwordx4 v[184:187], v[202:203], off
	global_load_dwordx4 v[188:191], v[202:203], off offset:256
	s_waitcnt vmcnt(5)
	v_mov_b32_e32 v158, v192
	v_mov_b32_e32 v159, v193
	v_mov_b32_e32 v160, v194
	v_mov_b32_e32 v161, v195
	v_lshlrev_b32_e32 v168, 16, v158
	v_and_b32_e32 v169, 0xffff0000, v158
	v_lshlrev_b32_e32 v158, 16, v159
	v_and_b32_e32 v159, 0xffff0000, v159
	v_lshlrev_b32_e32 v170, 16, v160
	v_and_b32_e32 v171, 0xffff0000, v160
	v_lshlrev_b32_e32 v160, 16, v161
	v_and_b32_e32 v161, 0xffff0000, v161
	v_mov_b32_e32 v162, v196
	v_mov_b32_e32 v163, v197
	v_mov_b32_e32 v164, v198
	v_mov_b32_e32 v165, v199
	v_lshlrev_b32_e32 v172, 16, v162
	v_and_b32_e32 v173, 0xffff0000, v162
	v_lshlrev_b32_e32 v162, 16, v163
	v_and_b32_e32 v163, 0xffff0000, v163
	v_lshlrev_b32_e32 v174, 16, v164
	v_and_b32_e32 v175, 0xffff0000, v164
	v_lshlrev_b32_e32 v164, 16, v165
	v_and_b32_e32 v165, 0xffff0000, v165
	v_pk_add_f32 v[176:177], v[48:49], v[158:159]
	v_pk_add_f32 v[168:169], v[46:47], v[168:169]
	v_pk_add_f32 v[178:179], v[44:45], v[160:161]
	v_pk_add_f32 v[160:161], v[42:43], v[170:171]
	v_pk_add_f32 v[162:163], v[16:17], v[162:163]
	v_pk_add_f32 v[170:171], v[14:15], v[172:173]
	v_pk_add_f32 v[164:165], v[12:13], v[164:165]
	v_pk_add_f32 v[172:173], v[10:11], v[174:175]
	v_mul_f32_e32 v149, v169, v169
	v_mul_f32_e32 v174, v177, v177
	v_mul_f32_e32 v175, v161, v161
	v_mul_f32_e32 v180, v179, v179
	v_cvt_pk_bf16_f32 v158, v168, v169
	v_cvt_pk_bf16_f32 v159, v176, v177
	v_mul_f32_e32 v169, v171, v171
	v_mul_f32_e32 v177, v163, v163
	v_mul_f32_e32 v181, v173, v173
	v_mul_f32_e32 v182, v165, v165
	v_fmac_f32_e32 v149, v168, v168
	v_fmac_f32_e32 v174, v176, v176
	v_fmac_f32_e32 v175, v160, v160
	v_fmac_f32_e32 v180, v178, v178
	v_fmac_f32_e32 v169, v170, v170
	v_fmac_f32_e32 v177, v162, v162
	v_fmac_f32_e32 v181, v172, v172
	v_fmac_f32_e32 v182, v164, v164
	v_add_f32_e32 v149, v149, v174
	v_add_f32_e32 v168, v175, v180
	v_add_f32_e32 v169, v169, v177
	v_add_f32_e32 v174, v181, v182
	v_add_f32_e32 v149, v149, v168
	v_add_f32_e32 v168, v169, v174
	v_add_f32_e32 v149, v149, v168
	ds_bpermute_b32 v168, v156, v149
	v_cvt_pk_bf16_f32 v160, v160, v161
	v_cvt_pk_bf16_f32 v161, v178, v179
	global_store_dwordx4 v[166:167], v[158:161], off sc1
	s_waitcnt lgkmcnt(0)
	v_add_f32_e32 v149, v149, v168
	ds_bpermute_b32 v158, v157, v149
	v_cvt_pk_bf16_f32 v160, v170, v171
	v_cvt_pk_bf16_f32 v161, v162, v163
	v_cvt_pk_bf16_f32 v162, v172, v173
	v_cvt_pk_bf16_f32 v163, v164, v165
	global_store_dwordx4 v[166:167], v[160:163], off offset:256 sc1
	s_and_saveexec_b64 s[40:41], s[4:5]
	s_cbranch_execz .LBB0_810
	v_lshlrev_b64 v[150:151], 6, v[150:151]
	v_lshl_add_u64 v[150:151], s[16:17], 0, v[150:151]
	v_lshl_add_u64 v[150:151], s[38:39], 2, v[150:151]
	s_lshl_b32 s20, s59, 2
	v_lshl_add_u64 v[150:151], v[150:151], 0, s[20:21]
	s_waitcnt lgkmcnt(0)
	v_add_f32_e32 v149, v149, v158
	global_store_dword v[150:151], v149, off sc1
.LBB0_810:
	s_or_b64 exec, exec, s[40:41]
	v_add_u32_e32 v148, 0xb0, v148
	v_ashrrev_i32_e32 v149, 31, v148
	v_lshlrev_b64 v[150:151], 11, v[148:149]
	v_lshl_add_u64 v[150:151], s[62:63], 0, v[150:151]
	v_lshl_add_u64 v[150:151], v[146:147], 1, v[150:151]
	s_waitcnt lgkmcnt(0)
	s_waitcnt vmcnt(3)
	v_mov_b32_e32 v158, v184
	v_mov_b32_e32 v159, v185
	v_mov_b32_e32 v160, v186
	v_mov_b32_e32 v161, v187
	v_lshlrev_b32_e32 v146, 16, v158
	v_and_b32_e32 v147, 0xffff0000, v158
	v_lshlrev_b32_e32 v158, 16, v159
	v_and_b32_e32 v159, 0xffff0000, v159
	v_lshlrev_b32_e32 v166, 16, v160
	v_and_b32_e32 v167, 0xffff0000, v160
	v_lshlrev_b32_e32 v160, 16, v161
	v_and_b32_e32 v161, 0xffff0000, v161
	v_mov_b32_e32 v162, v188
	v_mov_b32_e32 v163, v189
	v_mov_b32_e32 v164, v190
	v_mov_b32_e32 v165, v191
	v_lshlrev_b32_e32 v168, 16, v162
	v_and_b32_e32 v169, 0xffff0000, v162
	v_lshlrev_b32_e32 v162, 16, v163
	v_and_b32_e32 v163, 0xffff0000, v163
	v_lshlrev_b32_e32 v170, 16, v164
	v_and_b32_e32 v171, 0xffff0000, v164
	v_lshlrev_b32_e32 v164, 16, v165
	v_and_b32_e32 v165, 0xffff0000, v165
	v_pk_add_f32 v[172:173], v[40:41], v[158:159]
	v_pk_add_f32 v[146:147], v[38:39], v[146:147]
	v_pk_add_f32 v[174:175], v[36:37], v[160:161]
	v_pk_add_f32 v[160:161], v[34:35], v[166:167]
	v_pk_add_f32 v[162:163], v[8:9], v[162:163]
	v_pk_add_f32 v[166:167], v[6:7], v[168:169]
	v_pk_add_f32 v[164:165], v[4:5], v[164:165]
	v_pk_add_f32 v[168:169], v[2:3], v[170:171]
	v_mul_f32_e32 v170, v147, v147
	v_mul_f32_e32 v171, v173, v173
	v_mul_f32_e32 v176, v161, v161
	v_mul_f32_e32 v177, v175, v175
	v_cvt_pk_bf16_f32 v158, v146, v147
	v_cvt_pk_bf16_f32 v159, v172, v173
	v_mul_f32_e32 v147, v167, v167
	v_mul_f32_e32 v173, v163, v163
	v_mul_f32_e32 v178, v169, v169
	v_mul_f32_e32 v179, v165, v165
	v_fmac_f32_e32 v170, v146, v146
	v_fmac_f32_e32 v171, v172, v172
	v_fmac_f32_e32 v176, v160, v160
	v_fmac_f32_e32 v177, v174, v174
	v_fmac_f32_e32 v147, v166, v166
	v_fmac_f32_e32 v173, v162, v162
	v_fmac_f32_e32 v178, v168, v168
	v_fmac_f32_e32 v179, v164, v164
	v_add_f32_e32 v146, v170, v171
	v_add_f32_e32 v170, v176, v177
	v_add_f32_e32 v147, v147, v173
	v_add_f32_e32 v171, v178, v179
	v_add_f32_e32 v146, v146, v170
	v_add_f32_e32 v147, v147, v171
	v_add_f32_e32 v146, v146, v147
	ds_bpermute_b32 v147, v156, v146
	v_cvt_pk_bf16_f32 v160, v160, v161
	v_cvt_pk_bf16_f32 v161, v174, v175
	global_store_dwordx4 v[150:151], v[158:161], off sc1
	v_cvt_pk_bf16_f32 v156, v166, v167
	s_waitcnt lgkmcnt(0)
	v_add_f32_e32 v146, v146, v147
	ds_bpermute_b32 v147, v157, v146
	v_cvt_pk_bf16_f32 v157, v162, v163
	v_cvt_pk_bf16_f32 v158, v168, v169
	v_cvt_pk_bf16_f32 v159, v164, v165
	global_store_dwordx4 v[150:151], v[156:159], off offset:256 sc1
	s_and_saveexec_b64 s[40:41], s[4:5]
	s_cbranch_execz .LBB0_812
	v_lshlrev_b64 v[148:149], 6, v[148:149]
	v_lshl_add_u64 v[148:149], s[16:17], 0, v[148:149]
	v_lshl_add_u64 v[148:149], s[38:39], 2, v[148:149]
	s_lshl_b32 s20, s59, 2
	v_lshl_add_u64 v[148:149], v[148:149], 0, s[20:21]
	s_waitcnt lgkmcnt(0)
	v_add_f32_e32 v146, v146, v147
	global_store_dword v[148:149], v146, off sc1
